# HGRN2 prompt pass: batched (3-wide) ds_bpermute row-sum reductions in the fix pass, dead denormal/inf handling removed from per-chunk logs, chunk-top vmcnt waits counted past the younger RAW stores; p
# speedup vs baseline: 1.0063x; 1.0035x over previous
.LBB0_1408:
	s_lshl_b32 s6, s58, 1
	s_add_i32 s85, s6, 0
	s_lshl_b32 s6, s33, 9
	s_ashr_i32 s51, s33, 1
	s_lshl_b32 s56, s33, 4
	s_add_i32 s84, s85, 0x19a00
	s_add_i32 s85, s85, 0x15200
	s_add_i32 s76, s6, 0
	s_cmp_eq_u32 s51, 2
	s_cselect_b64 s[6:7], -1, 0
	s_and_b64 s[8:9], s[6:7], exec
	s_cselect_b32 s12, 48, 0x60
	s_cmp_eq_u32 s51, 1
	s_cselect_b64 s[8:9], -1, 0
	s_and_b64 s[10:11], s[8:9], exec
	s_cselect_b32 s10, 16, s12
	s_cmp_gt_u32 s33, 1
	s_cselect_b32 s64, s10, 0
	s_cmp_eq_u32 s33, 0
	s_cselect_b64 s[54:55], -1, 0
	s_and_b32 s68, s33, 3
	s_lshl_b32 s10, s68, 5
	s_add_i32 s77, s10, 0
	s_add_i32 s77, s77, 0x1e200
	s_lshl_b32 s88, s68, 4
	s_ashr_i32 s57, s56, 31
	s_cmp_eq_u32 s33, 1
	s_cselect_b64 s[10:11], -1, 0
	s_cmp_eq_u32 s33, 2
	s_cselect_b64 s[12:13], -1, 0
	s_cmp_eq_u32 s33, 3
	s_cselect_b64 s[14:15], -1, 0
	s_cmp_eq_u32 s33, 4
	s_cselect_b64 s[16:17], -1, 0
	s_cmp_eq_u32 s33, 5
	s_cselect_b64 s[18:19], -1, 0
	s_cmp_eq_u32 s33, 6
	s_cselect_b64 s[20:21], -1, 0
	s_cmp_eq_u32 s33, 7
	s_cselect_b64 s[22:23], -1, 0
	s_cmp_eq_u32 s51, 3
	s_cselect_b64 s[24:25], -1, 0
	v_writelane_b32 v254, s58, 45
	s_add_i32 s36, s64, s58
	s_cmp_lt_i32 s51, 1
	v_writelane_b32 v254, s59, 46
	s_cselect_b64 s[58:59], -1, 0
	s_cmp_lt_i32 s51, 2
	s_cselect_b64 s[60:61], -1, 0
	s_cmp_lt_i32 s51, 3
	v_writelane_b32 v254, s36, 47
	s_cselect_b64 s[62:63], -1, 0
	s_add_i32 s50, s30, s64
	s_add_i32 s51, s34, s64
	s_add_i32 s89, s48, s64
	s_add_i32 s36, s96, s64
	s_add_i32 s72, s4, s64
	s_add_i32 s87, s2, s64
	s_add_i32 s73, s90, s64
	s_ashr_i32 s69, s33, 2
	s_cmp_le_i32 s68, s69
	s_cselect_b64 s[64:65], -1, 0
	s_cmp_eq_u32 s69, 2
	s_cselect_b32 s70, 48, 0x60
	s_cmp_lg_u32 s69, 1
	s_cselect_b32 s70, s70, 16
	s_cmp_gt_u32 s33, 3
	v_writelane_b32 v254, s36, 48
	s_cselect_b32 s36, s70, 0
	s_lshl_b32 s86, s69, 4
	s_cmp_eq_u32 s69, s68
	v_writelane_b32 v254, s36, 49
	s_cselect_b64 s[36:37], -1, 0
	s_add_i32 s69, s33, 8
	s_ashr_i32 s74, s69, 2
	s_cmp_le_i32 s68, s74
	s_cselect_b64 s[70:71], -1, 0
	s_cmp_eq_u32 s74, 2
	s_cselect_b32 s75, 48, 0x60
	s_cmp_lg_u32 s74, 1
	v_writelane_b32 v254, s36, 51
	s_cselect_b32 s75, s75, 16
	s_cmp_gt_u32 s69, 3
	v_writelane_b32 v254, s37, 52
	s_cselect_b32 s36, s75, 0
	s_lshl_b32 s82, s74, 4
	s_cmp_eq_u32 s74, s68
	v_writelane_b32 v254, s36, 53
	s_cselect_b64 s[36:37], -1, 0
	v_writelane_b32 v254, s36, 54
	s_lshl_b64 s[68:69], s[44:45], 25
	v_mov_b32_e32 v50, 0
	v_writelane_b32 v254, s37, 55
	v_lshrrev_b32_e32 v98, 4, v86
	v_readlane_b32 s36, v254, 23
	v_readlane_b32 s37, v254, 24
	s_lshl_b64 s[74:75], s[36:37], 23
	s_add_u32 s68, s68, s74
	s_addc_u32 s74, s69, s75
	s_lshl_b32 s69, s52, 9
	s_or_b32 s68, s68, s69
	s_lshl_b64 s[78:79], s[56:57], 2
	v_writelane_b32 v254, s68, 56
	s_add_u32 s57, s68, s78
	v_writelane_b32 v254, s74, 57
	v_writelane_b32 v254, s78, 58
	s_addc_u32 s68, s74, s79
	s_add_u32 s46, s46, s57
	s_addc_u32 s47, s47, s68
	s_add_u32 s74, s46, 0x6cb30000
	s_addc_u32 s75, s47, 0
	s_add_u32 s40, s40, 0x27620000
	s_addc_u32 s41, s41, 0
	s_lshl_b64 s[44:45], s[44:45], 24
	s_lshl_b64 s[46:47], s[36:37], 22
	s_mov_b32 s36, s33
	s_add_u32 s33, s44, s46
	s_addc_u32 s37, s45, s47
	s_lshl_b64 s[44:45], s[90:91], 11
	v_writelane_b32 v254, s79, 59
	s_add_u32 s44, s33, s44
	s_addc_u32 s45, s37, s45
	v_writelane_b32 v254, s52, 60
	s_lshl_b32 s52, s52, 8
	s_or_b32 s44, s44, s52
	s_add_u32 s46, s40, s44
	s_addc_u32 s47, s41, s45
	v_writelane_b32 v254, s46, 61
	v_and_b32_e32 v83, 15, v86
	s_mulk_i32 s50, 0x110
	v_writelane_b32 v254, s47, 62
	s_add_u32 s46, s38, 0x2b720000
	s_addc_u32 s47, s39, 0
	s_add_u32 s38, s46, s44
	s_addc_u32 s39, s47, s45
	s_add_u32 s57, s0, 0x2f820000
	s_addc_u32 s83, s1, 0
	s_add_u32 s0, s57, s44
	v_writelane_b32 v254, s38, 63
	s_addc_u32 s1, s83, s45
	s_mulk_i32 s51, 0x110
	v_writelane_b32 v255, s39, 0
	s_add_u32 s38, s42, 0x5c300000
	v_writelane_b32 v255, s0, 1
	s_addc_u32 s39, s43, 0
	s_mulk_i32 s89, 0x110
	v_writelane_b32 v255, s1, 2
	s_add_u32 s0, s90, s26
	s_addc_u32 s1, s91, s27
	s_add_u32 s0, s0, s28
	s_addc_u32 s1, s1, s29
	s_lshl_b64 s[0:1], s[0:1], 11
	s_or_b32 s0, s0, s52
	s_add_u32 s92, s38, s0
	s_addc_u32 s93, s39, s1
	s_lshl_b64 s[0:1], s[2:3], 11
	s_add_u32 s0, s33, s0
	s_addc_u32 s1, s37, s1
	s_or_b32 s0, s0, s52
	s_add_u32 s42, s40, s0
	s_addc_u32 s43, s41, s1
	v_writelane_b32 v255, s42, 3
	s_mul_i32 s91, s34, 0x110
	s_mulk_i32 s87, 0x110
	v_writelane_b32 v255, s43, 4
	s_add_u32 s42, s46, s0
	s_addc_u32 s43, s47, s1
	v_writelane_b32 v255, s42, 5
	s_add_u32 s0, s57, s0
	s_addc_u32 s1, s83, s1
	v_writelane_b32 v255, s43, 6
	v_writelane_b32 v255, s0, 7
	v_mov_b32_e32 v51, v50
	v_mov_b32_e32 v52, v50
	v_writelane_b32 v255, s1, 8
	s_add_u32 s0, s2, s26
	s_addc_u32 s1, s3, s27
	s_add_u32 s0, s0, s28
	s_addc_u32 s1, s1, s29
	s_lshl_b64 s[0:1], s[0:1], 11
	s_or_b32 s0, s0, s52
	s_add_u32 s44, s38, s0
	s_addc_u32 s45, s39, s1
	s_lshl_b64 s[0:1], s[4:5], 11
	s_add_u32 s0, s33, s0
	s_addc_u32 s1, s37, s1
	s_or_b32 s0, s0, s52
	s_add_u32 s42, s40, s0
	s_addc_u32 s43, s41, s1
	v_writelane_b32 v255, s42, 9
	v_mov_b32_e32 v53, v50
	v_mov_b32_e32 v54, v50
	v_writelane_b32 v255, s43, 10
	s_add_u32 s42, s46, s0
	s_addc_u32 s43, s47, s1
	v_writelane_b32 v255, s42, 11
	s_add_u32 s0, s57, s0
	s_addc_u32 s1, s83, s1
	v_writelane_b32 v255, s43, 12
	v_writelane_b32 v255, s0, 13
	v_mov_b32_e32 v55, v50
	v_mov_b32_e32 v56, v50
	v_writelane_b32 v255, s1, 14
	s_add_u32 s0, s4, s26
	s_addc_u32 s1, s5, s27
	s_add_u32 s0, s0, s28
	s_addc_u32 s1, s1, s29
	s_lshl_b64 s[0:1], s[0:1], 11
	s_or_b32 s0, s0, s52
	s_add_u32 s94, s38, s0
	s_addc_u32 s95, s39, s1
	s_lshl_b64 s[0:1], s[96:97], 11
	s_add_u32 s0, s33, s0
	s_addc_u32 s1, s37, s1
	s_or_b32 s0, s0, s52
	s_add_u32 s42, s40, s0
	s_addc_u32 s43, s41, s1
	v_writelane_b32 v255, s42, 15
	v_mov_b32_e32 v57, v50
	v_mov_b32_e32 v42, v50
	v_writelane_b32 v255, s43, 16
	s_add_u32 s42, s46, s0
	s_addc_u32 s43, s47, s1
	v_writelane_b32 v255, s42, 17
	s_add_u32 s0, s57, s0
	s_addc_u32 s1, s83, s1
	v_writelane_b32 v255, s43, 18
	v_writelane_b32 v255, s0, 19
	v_mov_b32_e32 v43, v50
	v_mov_b32_e32 v44, v50
	v_writelane_b32 v255, s1, 20
	s_add_u32 s0, s96, s26
	s_addc_u32 s1, s97, s27
	s_add_u32 s0, s0, s28
	s_addc_u32 s1, s1, s29
	s_lshl_b64 s[0:1], s[0:1], 11
	s_or_b32 s0, s0, s52
	s_add_u32 s42, s38, s0
	s_addc_u32 s43, s39, s1
	s_lshl_b64 s[0:1], s[48:49], 11
	s_add_u32 s0, s33, s0
	s_addc_u32 s1, s37, s1
	s_or_b32 s0, s0, s52
	s_add_u32 s68, s40, s0
	s_addc_u32 s69, s41, s1
	v_writelane_b32 v255, s68, 21
	s_mul_i32 s97, s48, 0x88
	v_mov_b32_e32 v45, v50
	v_writelane_b32 v255, s69, 22
	s_add_u32 s68, s46, s0
	s_addc_u32 s69, s47, s1
	v_writelane_b32 v255, s68, 23
	s_add_u32 s0, s57, s0
	s_addc_u32 s1, s83, s1
	v_writelane_b32 v255, s69, 24
	v_writelane_b32 v255, s0, 25
	v_mov_b32_e32 v46, v50
	v_mov_b32_e32 v47, v50
	v_writelane_b32 v255, s1, 26
	s_add_u32 s0, s48, s26
	s_addc_u32 s1, s49, s27
	s_add_u32 s0, s0, s28
	s_addc_u32 s1, s1, s29
	s_lshl_b64 s[0:1], s[0:1], 11
	s_or_b32 s0, s0, s52
	s_add_u32 s68, s38, s0
	s_addc_u32 s69, s39, s1
	s_lshl_b64 s[0:1], s[34:35], 11
	s_add_u32 s0, s33, s0
	s_addc_u32 s1, s37, s1
	s_or_b32 s0, s0, s52
	s_add_u32 s78, s40, s0
	s_addc_u32 s79, s41, s1
	v_writelane_b32 v255, s78, 27
	s_mul_i32 s49, s30, 0x110
	s_mulk_i32 s48, 0x110
	v_writelane_b32 v255, s79, 28
	s_add_u32 s78, s46, s0
	s_addc_u32 s79, s47, s1
	v_writelane_b32 v255, s78, 29
	s_add_u32 s0, s57, s0
	s_addc_u32 s1, s83, s1
	v_writelane_b32 v255, s79, 30
	v_writelane_b32 v255, s0, 31
	v_mov_b32_e32 v48, v50
	v_mov_b32_e32 v49, v50
	v_writelane_b32 v255, s1, 32
	s_add_u32 s0, s34, s26
	s_addc_u32 s1, s35, s27
	s_add_u32 s0, s0, s28
	s_addc_u32 s1, s1, s29
	s_lshl_b64 s[0:1], s[0:1], 11
	s_or_b32 s0, s0, s52
	s_add_u32 s78, s38, s0
	s_addc_u32 s79, s39, s1
	s_lshl_b64 s[0:1], s[30:31], 11
	s_add_u32 s0, s33, s0
	s_addc_u32 s1, s37, s1
	s_or_b32 s0, s0, s52
	s_add_u32 vcc_lo, s40, s0
	s_addc_u32 vcc_hi, s41, s1
	v_writelane_b32 v255, vcc_lo, 33
	v_mov_b32_e32 v30, v50
	v_mov_b32_e32 v31, v50
	v_writelane_b32 v255, vcc_hi, 34
	s_add_u32 vcc_lo, s46, s0
	s_addc_u32 vcc_hi, s47, s1
	v_writelane_b32 v255, vcc_lo, 35
	s_add_u32 s0, s57, s0
	s_addc_u32 s1, s83, s1
	v_writelane_b32 v255, vcc_hi, 36
	v_writelane_b32 v255, s0, 37
	v_mov_b32_e32 v32, v50
	v_mov_b32_e32 v33, v50
	v_writelane_b32 v255, s1, 38
	s_add_u32 s0, s30, s26
	s_addc_u32 s1, s31, s27
	s_add_u32 s0, s0, s28
	s_addc_u32 s1, s1, s29
	s_lshl_b64 s[0:1], s[0:1], 11
	s_or_b32 s0, s0, s52
	s_add_u32 s0, s38, s0
	s_addc_u32 s1, s39, s1
	s_lshl_b64 vcc, s[66:67], 11
	s_add_u32 s3, s33, vcc_lo
	s_addc_u32 s5, s37, vcc_hi
	s_or_b32 s3, s3, s52
	v_writelane_b32 v255, s33, 39
	s_add_u32 s40, s40, s3
	v_writelane_b32 v255, s37, 40
	s_addc_u32 s41, s41, s5
	v_writelane_b32 v255, s40, 41
	s_mul_i32 s33, s36, 0x880
	v_mov_b32_e32 v38, v50
	v_writelane_b32 v255, s41, 42
	s_add_u32 s40, s46, s3
	s_addc_u32 s41, s47, s5
	v_writelane_b32 v255, s40, 43
	s_mul_i32 s47, s2, 0x88
	s_mul_i32 s46, s4, 0x88
	v_writelane_b32 v255, s41, 44
	s_add_u32 s40, s57, s3
	s_addc_u32 s41, s83, s5
	s_add_u32 s3, s66, s26
	s_addc_u32 s5, s67, s27
	s_add_u32 s26, s3, s28
	s_addc_u32 s27, s5, s29
	v_writelane_b32 v255, s40, 45
	s_lshl_b64 s[26:27], s[26:27], 11
	s_or_b32 s3, s26, s52
	v_writelane_b32 v255, s41, 46
	v_writelane_b32 v255, s52, 47
	s_add_u32 s52, s38, s3
	s_mul_i32 s40, s2, 0x110
	v_readlane_b32 s2, v254, 47
	s_addc_u32 s53, s39, s27
	s_mul_i32 s38, s2, 0x110
	s_mul_i32 s39, s36, 0x440
	v_readlane_b32 s2, v254, 48
	v_readlane_b32 s36, v254, 43
	s_mul_i32 s5, s30, 0x88
	s_mul_i32 s83, s34, 0x88
	s_mul_i32 s57, s96, 0x88
	s_mulk_i32 s96, 0x110
	s_mulk_i32 s4, 0x110
	s_mul_i32 s41, s90, 0x88
	s_mulk_i32 s90, 0x110
	s_mul_i32 s66, s2, 0x110
	s_mul_i32 s67, s72, 0x110
	s_mul_i32 s72, s73, 0x110
	v_mov_b32_e32 v39, v50
	v_mov_b32_e32 v40, v50
	v_mov_b32_e32 v41, v50
	v_mov_b32_e32 v26, v50
	v_mov_b32_e32 v27, v50
	v_mov_b32_e32 v28, v50
	v_mov_b32_e32 v29, v50
	v_mov_b32_e32 v34, v50
	v_mov_b32_e32 v35, v50
	v_mov_b32_e32 v36, v50
	v_mov_b32_e32 v37, v50
	v_mov_b32_e32 v84, v50
	v_mov_b32_e32 v85, v50
	s_mov_b64 s[34:35], 0
	s_movk_i32 s73, 0x90
	v_readlane_b32 s37, v254, 44
	s_waitcnt vmcnt(0)
	s_branch .LBB0_1410

.LBB0_1410:
	s_waitcnt vmcnt(38)
	v_lshlrev_b32_e32 v101, 16, v16
	v_sub_f32_e32 v58, 1.0, v101
	v_max_f32_e32 v58, 0x3a800000, v58
	s_mov_b32 s2, 0x800000
	s_mov_b32 s3, 0x3f317217
	s_mov_b32 s28, 0x7f800000
	v_log_f32_e32 v58, v58
	v_and_b32_e32 v104, 0xffff0000, v16
	s_waitcnt vmcnt(36)
	v_lshlrev_b32_e32 v102, 16, v17
	v_and_b32_e32 v105, 0xffff0000, v17
	v_mul_f32_e32 v59, 0x3f317217, v58
	v_fma_f32 v59, v58, s3, -v59
	v_fmac_f32_e32 v59, 0x3377d1cf, v58
	v_fmac_f32_e32 v59, 0x3f317217, v58
	s_waitcnt vmcnt(32)
	v_lshlrev_b32_e32 v103, 16, v18
	v_and_b32_e32 v107, 0xffff0000, v18
	v_mov_b32_e32 v58, v59

	v_sub_f32_e32 v59, 1.0, v104
	v_max_f32_e32 v59, 0x3a800000, v59
	s_waitcnt vmcnt(30)
	v_lshlrev_b32_e32 v106, 16, v19
	v_and_b32_e32 v109, 0xffff0000, v19
	v_log_f32_e32 v59, v59
	s_waitcnt vmcnt(26)
	v_lshlrev_b32_e32 v108, 16, v20
	v_and_b32_e32 v112, 0xffff0000, v20
	s_waitcnt vmcnt(24)
	v_lshlrev_b32_e32 v110, 16, v21
	v_mul_f32_e32 v60, 0x3f317217, v59
	v_fma_f32 v60, v59, s3, -v60
	v_fmac_f32_e32 v60, 0x3377d1cf, v59
	v_fmac_f32_e32 v60, 0x3f317217, v59
	v_and_b32_e32 v114, 0xffff0000, v21
	s_waitcnt vmcnt(19)
	v_lshlrev_b32_e32 v113, 16, v22
	v_mov_b32_e32 v59, v60

	v_pk_add_f32 v[62:63], v[58:59], 0 op_sel_hi:[1,0]
	v_sub_f32_e32 v58, 1.0, v102
	v_max_f32_e32 v58, 0x3a800000, v58
	v_and_b32_e32 v116, 0xffff0000, v22
	s_waitcnt vmcnt(18)
	v_lshlrev_b32_e32 v115, 16, v23
	v_log_f32_e32 v58, v58
	v_and_b32_e32 v117, 0xffff0000, v23
	v_mov_b32_e32 v99, v83
	v_mov_b32_e32 v0, v82
	v_mul_f32_e32 v59, 0x3f317217, v58
	v_fma_f32 v59, v58, s3, -v59
	v_fmac_f32_e32 v59, 0x3377d1cf, v58
	v_fmac_f32_e32 v59, 0x3f317217, v58
	v_mov_b32_e32 v100, v98

	v_mov_b32_e32 v58, v59

	v_sub_f32_e32 v59, 1.0, v105
	v_max_f32_e32 v59, 0x3a800000, v59

	v_log_f32_e32 v59, v59
	s_nop 0
	v_mul_f32_e32 v60, 0x3f317217, v59
	v_fma_f32 v60, v59, s3, -v60
	v_fmac_f32_e32 v60, 0x3377d1cf, v59
	v_fmac_f32_e32 v60, 0x3f317217, v59

	v_mov_b32_e32 v59, v60

	v_sub_f32_e32 v60, 1.0, v103
	v_max_f32_e32 v60, 0x3a800000, v60
	v_pk_add_f32 v[58:59], v[58:59], v[62:63]

	v_log_f32_e32 v60, v60
	s_nop 0
	v_mul_f32_e32 v61, 0x3f317217, v60
	v_fma_f32 v61, v60, s3, -v61
	v_fmac_f32_e32 v61, 0x3377d1cf, v60
	v_fmac_f32_e32 v61, 0x3f317217, v60

	v_mov_b32_e32 v60, v61

	v_sub_f32_e32 v61, 1.0, v107
	v_max_f32_e32 v61, 0x3a800000, v61

	v_log_f32_e32 v61, v61
	s_nop 0
	v_mul_f32_e32 v64, 0x3f317217, v61
	v_fma_f32 v64, v61, s3, -v64
	v_fmac_f32_e32 v64, 0x3377d1cf, v61
	v_fmac_f32_e32 v64, 0x3f317217, v61
	s_nop 1
	v_mov_b32_e32 v61, v64

	v_sub_f32_e32 v64, 1.0, v106
	v_max_f32_e32 v64, 0x3a800000, v64
	v_pk_add_f32 v[60:61], v[60:61], v[58:59]

	v_log_f32_e32 v64, v64
	s_nop 0
	v_mul_f32_e32 v65, 0x3f317217, v64
	v_fma_f32 v65, v64, s3, -v65
	v_fmac_f32_e32 v65, 0x3377d1cf, v64
	v_fmac_f32_e32 v65, 0x3f317217, v64
	s_nop 1
	v_mov_b32_e32 v64, v65

	v_sub_f32_e32 v65, 1.0, v109
	v_max_f32_e32 v65, 0x3a800000, v65

	v_log_f32_e32 v65, v65
	s_nop 0
	v_mul_f32_e32 v66, 0x3f317217, v65
	v_fma_f32 v66, v65, s3, -v66
	v_fmac_f32_e32 v66, 0x3377d1cf, v65
	v_fmac_f32_e32 v66, 0x3f317217, v65
	s_nop 1
	v_mov_b32_e32 v65, v66

	v_pk_add_f32 v[66:67], v[64:65], v[60:61]
	v_sub_f32_e32 v64, 1.0, v108
	v_max_f32_e32 v64, 0x3a800000, v64

	v_log_f32_e32 v64, v64
	s_nop 0
	v_mul_f32_e32 v65, 0x3f317217, v64
	v_fma_f32 v65, v64, s3, -v65
	v_fmac_f32_e32 v65, 0x3377d1cf, v64
	v_fmac_f32_e32 v65, 0x3f317217, v64
	s_nop 1
	v_mov_b32_e32 v64, v65

	v_sub_f32_e32 v65, 1.0, v112
	v_max_f32_e32 v65, 0x3a800000, v65

	v_log_f32_e32 v65, v65
	s_nop 0
	v_mul_f32_e32 v68, 0x3f317217, v65
	v_fma_f32 v68, v65, s3, -v68
	v_fmac_f32_e32 v68, 0x3377d1cf, v65
	v_fmac_f32_e32 v68, 0x3f317217, v65
	s_nop 1
	v_mov_b32_e32 v65, v68

	v_pk_add_f32 v[68:69], v[64:65], v[66:67]
	v_sub_f32_e32 v64, 1.0, v110
	v_max_f32_e32 v64, 0x3a800000, v64

	v_log_f32_e32 v64, v64
	s_nop 0
	v_mul_f32_e32 v65, 0x3f317217, v64
	v_fma_f32 v65, v64, s3, -v65
	v_fmac_f32_e32 v65, 0x3377d1cf, v64
	v_fmac_f32_e32 v65, 0x3f317217, v64
	s_nop 1
	v_mov_b32_e32 v64, v65

	v_sub_f32_e32 v65, 1.0, v114
	v_max_f32_e32 v65, 0x3a800000, v65

	v_log_f32_e32 v65, v65
	s_nop 0
	v_mul_f32_e32 v70, 0x3f317217, v65
	v_fma_f32 v70, v65, s3, -v70
	v_fmac_f32_e32 v70, 0x3377d1cf, v65
	v_fmac_f32_e32 v70, 0x3f317217, v65
	s_nop 1
	v_mov_b32_e32 v65, v70

	v_pk_add_f32 v[70:71], v[64:65], v[68:69]
	v_sub_f32_e32 v64, 1.0, v113
	v_max_f32_e32 v64, 0x3a800000, v64

	v_log_f32_e32 v64, v64
	s_nop 0
	v_mul_f32_e32 v65, 0x3f317217, v64
	v_fma_f32 v65, v64, s3, -v65
	v_fmac_f32_e32 v65, 0x3377d1cf, v64
	v_fmac_f32_e32 v65, 0x3f317217, v64
	s_nop 1
	v_mov_b32_e32 v64, v65

	v_sub_f32_e32 v65, 1.0, v116
	v_max_f32_e32 v65, 0x3a800000, v65

	v_log_f32_e32 v65, v65
	s_nop 0
	v_mul_f32_e32 v72, 0x3f317217, v65
	v_fma_f32 v72, v65, s3, -v72
	v_fmac_f32_e32 v72, 0x3377d1cf, v65
	v_fmac_f32_e32 v72, 0x3f317217, v65
	s_nop 1
	v_mov_b32_e32 v65, v72

	v_pk_add_f32 v[72:73], v[64:65], v[70:71]
	v_sub_f32_e32 v64, 1.0, v115
	v_max_f32_e32 v64, 0x3a800000, v64

	v_log_f32_e32 v64, v64
	s_nop 0
	v_mul_f32_e32 v65, 0x3f317217, v64
	v_fma_f32 v65, v64, s3, -v65
	v_fmac_f32_e32 v65, 0x3377d1cf, v64
	v_fmac_f32_e32 v65, 0x3f317217, v64
	s_nop 1
	v_mov_b32_e32 v64, v65

	v_sub_f32_e32 v65, 1.0, v117
	v_max_f32_e32 v65, 0x3a800000, v65

	v_log_f32_e32 v65, v65
	s_nop 0
	v_mul_f32_e32 v74, 0x3f317217, v65
	v_fma_f32 v74, v65, s3, -v74
	v_fmac_f32_e32 v74, 0x3377d1cf, v65
	v_fmac_f32_e32 v74, 0x3f317217, v65
	s_nop 1
	v_mov_b32_e32 v65, v74

	v_pk_add_f32 v[74:75], v[64:65], v[72:73]
	v_lshlrev_b32_e32 v64, 2, v0
	v_add_u32_e32 v65, s76, v64
	ds_write_b64 v65, v[74:75]
	s_waitcnt lgkmcnt(0)
	s_barrier
	v_add_u32_e32 v111, 0, v64
	ds_read2st64_b64 v[76:79], v111 offset1:1
	s_andn2_b64 vcc, exec, s[58:59]
	s_waitcnt lgkmcnt(0)
	v_pk_add_f32 v[64:65], v[76:77], 0 op_sel_hi:[1,0]
	s_nop 0
	v_pk_add_f32 v[80:81], v[64:65], v[78:79]
	ds_read2st64_b64 v[76:79], v111 offset0:2 offset1:3
	v_cndmask_b32_e64 v86, 0, v65, s[10:11]
	v_cndmask_b32_e64 v87, 0, v64, s[10:11]
	s_waitcnt lgkmcnt(0)
	v_pk_add_f32 v[64:65], v[80:81], v[76:77]
	v_cndmask_b32_e64 v76, v87, v80, s[12:13]
	v_cndmask_b32_e64 v77, v86, v81, s[12:13]
	v_cndmask_b32_e64 v86, v77, v65, s[14:15]
	v_cndmask_b32_e64 v87, v76, v64, s[14:15]
	v_pk_add_f32 v[94:95], v[64:65], v[78:79]
	ds_read2st64_b64 v[76:79], v111 offset0:4 offset1:5
	s_waitcnt lgkmcnt(0)
	v_pk_add_f32 v[64:65], v[94:95], v[76:77]
	v_cndmask_b32_e64 v76, v87, v94, s[16:17]
	v_cndmask_b32_e64 v77, v86, v95, s[16:17]
	v_cndmask_b32_e64 v77, v77, v65, s[18:19]
	v_cndmask_b32_e64 v76, v76, v64, s[18:19]
	v_pk_add_f32 v[96:97], v[64:65], v[78:79]
	s_nop 0
	v_cndmask_b32_e64 v88, v76, v96, s[20:21]
	v_cndmask_b32_e64 v89, v77, v97, s[20:21]
	ds_read2st64_b64 v[76:79], v111 offset0:6 offset1:7
	s_waitcnt lgkmcnt(0)
	v_pk_add_f32 v[86:87], v[96:97], v[76:77]
	s_nop 0
	v_pk_add_f32 v[64:65], v[86:87], v[78:79]
	v_cndmask_b32_e64 v76, 0, v81, s[8:9]
	v_cndmask_b32_e64 v77, 0, v80, s[8:9]
	v_cndmask_b32_e64 v78, v81, v95, s[8:9]
	v_cndmask_b32_e64 v79, v80, v94, s[8:9]
	v_cndmask_b32_e64 v77, v77, v94, s[6:7]
	v_cndmask_b32_e64 v76, v76, v95, s[6:7]
	v_cndmask_b32_e64 v79, v79, v96, s[6:7]
	v_cndmask_b32_e64 v78, v78, v97, s[6:7]
	v_cndmask_b32_e64 v91, v76, v97, s[24:25]
	v_cndmask_b32_e64 v90, v77, v96, s[24:25]
	v_cndmask_b32_e64 v77, v78, v65, s[24:25]
	v_cndmask_b32_e64 v76, v79, v64, s[24:25]
	v_pk_add_f32 v[78:79], v[80:81], v[76:77] neg_lo:[0,1] neg_hi:[0,1]
	v_mul_f32_e32 v92, 0x3fb8aa3b, v90
	v_min_f32_e32 v78, 0, v78
	v_mul_f32_e32 v78, 0x3fb8aa3b, v78
	v_exp_f32_e32 v118, v78
	v_min_f32_e32 v78, 0, v79
	v_mul_f32_e32 v78, 0x3fb8aa3b, v78
	v_exp_f32_e32 v119, v78
	v_cndmask_b32_e64 v79, v89, v87, s[22:23]
	v_cndmask_b32_e64 v78, v88, v86, s[22:23]
	v_pk_add_f32 v[88:89], v[78:79], v[90:91] neg_lo:[0,1] neg_hi:[0,1]
	v_mul_f32_e32 v93, 0x3fb8aa3b, v91
	v_pk_add_f32 v[62:63], v[62:63], v[88:89]
	v_pk_add_f32 v[86:87], v[76:77], v[90:91] neg_lo:[0,1] neg_hi:[0,1]
	v_mul_f32_e32 v90, 0x3fb8aa3b, v62
	v_exp_f32_e32 v78, v93
	v_exp_f32_e32 v93, v90
	v_mul_f32_e32 v90, 0x3fb8aa3b, v63
	v_exp_f32_e32 v123, v90
	v_mul_f32_e32 v79, 0x3fb8aa3b, v84
	v_rcp_f32_e32 v90, v93
	v_exp_f32_e32 v80, v92
	v_exp_f32_e32 v92, v79
	v_mul_f32_e32 v79, 0x3fb8aa3b, v85
	v_exp_f32_e32 v122, v79
	v_min_f32_e32 v121, 0x79297b5a, v90
	v_rcp_f32_e32 v90, v123
	v_pk_add_f32 v[62:63], v[86:87], v[62:63] neg_lo:[0,1] neg_hi:[0,1]
	v_lshlrev_b32_e32 v79, 1, v0
	v_mul_f32_e32 v62, 0x3fb8aa3b, v62
	v_sub_u32_e32 v120, v111, v79
	v_lshlrev_b32_e32 v81, 16, v8
	v_and_b32_e32 v79, 0xffff0000, v8
	v_exp_f32_e32 v125, v62
	v_mul_f32_e32 v62, 0x3fb8aa3b, v63
	v_min_f32_e32 v124, 0x79297b5a, v90
	v_exp_f32_e32 v126, v62
	v_pk_mul_f32 v[90:91], v[92:93], v[80:81]
	v_pk_mul_f32 v[92:93], v[122:123], v[78:79]
	v_lshl_add_u32 v63, s39, 1, v120
	v_cvt_pk_bf16_f32 v62, v91, v93
	ds_write_b32 v63, v62 offset:8192
	v_mul_f32_e32 v62, v80, v91
	v_mul_f32_e32 v79, v78, v93
	v_cvt_pk_bf16_f32 v62, v62, v79
	ds_write_b32 v63, v62 offset:25600
	v_mul_f32_e32 v62, v90, v91
	v_mul_f32_e32 v63, v92, v93
	v_cvt_pk_bf16_f32 v79, v62, v63
	v_lshl_add_u64 v[62:63], v[0:1], 1, s[34:35]
	v_lshl_add_u64 v[122:123], s[52:53], 0, v[62:63]
	v_mul_f32_e32 v91, v121, v101
	v_mul_f32_e32 v93, v124, v104
	global_store_dword v[122:123], v79, off
	v_cvt_pk_bf16_f32 v91, v91, v93
	v_add_u32_e32 v93, s38, v120
	ds_write_b32 v93, v91 offset:43008
	v_cndmask_b32_e64 v91, 0, 1, s[58:59]
	v_mul_f32_e32 v79, v125, v101
	v_mul_f32_e32 v81, v126, v104
	v_cmp_ne_u32_e64 s[26:27], 1, v91
	v_add_u32_e32 v101, s33, v120
	s_cbranch_vccnz .LBB0_1412
	v_mul_f32_e32 v91, v119, v81
	v_mul_f32_e32 v93, v118, v79
	v_cvt_pk_bf16_f32 v91, v93, v91
	ds_write_b32 v101, v91 offset:47360

.LBB0_1498:
	s_waitcnt vmcnt(55)
	v_mfma_f32_16x16x32_bf16 v[54:57], v[94:97], v[2:5], v[54:57]
	v_mov_b32_e32 v220, v186
	v_mov_b32_e32 v0, v187
	v_mfma_f32_16x16x32_bf16 v[54:57], v[90:93], v[6:9], v[54:57]
	v_lshl_add_u64 v[222:223], v[114:115], 0, s[2:3]
	s_mov_b32 s8, 0x5c320000
	s_waitcnt vmcnt(54)
	v_mfma_f32_16x16x32_bf16 v[38:41], v[38:41], v[10:13], v[54:57]
	s_lshl_b32 s12, s18, 2
	s_waitcnt vmcnt(52)
	v_mfma_f32_16x16x32_bf16 v[110:113], v[18:21], v[14:17], v[38:41]
	v_lshl_add_u64 v[18:19], v[122:123], 0, s[2:3]
	global_load_ushort v204, v[18:19], off
	v_lshl_add_u64 v[54:55], s[0:1], 0, v[154:155]
	s_waitcnt vmcnt(11)
	v_mfma_f32_16x16x32_bf16 v[18:21], v[86:89], v[2:5], v[26:29]
	v_lshl_add_u64 v[38:39], s[0:1], 0, v[156:157]
	global_load_dword v54, v[54:55], off
	s_nop 0
	v_mul_f32_e32 v224, v110, v110
	v_mfma_f32_16x16x32_bf16 v[18:21], v[50:53], v[6:9], v[18:21]
	v_lshl_add_u64 v[26:27], v[124:125], 0, s[2:3]
	global_load_ushort v203, v[26:27], off
	global_load_dword v55, v[38:39], off
	s_waitcnt vmcnt(6)
	v_mfma_f32_16x16x32_bf16 v[18:21], v[82:85], v[10:13], v[18:21]
	v_mfma_f32_16x16x32_bf16 v[106:109], v[42:45], v[14:17], v[18:21]
	s_nop 6
	v_lshl_add_u64 v[18:19], v[128:129], 0, s[2:3]
	global_load_ushort v201, v[18:19], off
	v_mfma_f32_16x16x32_bf16 v[18:21], v[78:81], v[2:5], v[30:33]
	v_lshl_add_u64 v[26:27], s[0:1], 0, v[158:159]
	global_load_dword v56, v[26:27], off
	v_lshl_add_u64 v[26:27], v[126:127], 0, s[2:3]
	v_mfma_f32_16x16x32_bf16 v[18:21], v[46:49], v[6:9], v[18:21]
	global_load_ushort v202, v[26:27], off
	v_lshl_add_u64 v[26:27], s[0:1], 0, v[160:161]
	global_load_dword v57, v[26:27], off
	v_mfma_f32_16x16x32_bf16 v[28:31], v[66:69], v[10:13], v[18:21]
	v_add_co_u32_e32 v26, vcc, s8, v222
	s_and_b32 s8, s22, 0x200
	s_nop 0
	v_addc_co_u32_e32 v27, vcc, 0, v223, vcc
	v_mfma_f32_16x16x32_bf16 v[102:105], v[22:25], v[14:17], v[28:31]
	v_lshl_add_u64 v[22:23], v[130:131], 0, s[2:3]
	global_load_dwordx2 v[94:95], v[26:27], off
	global_load_dwordx2 v[96:97], v[26:27], off offset:32
	global_load_dwordx2 v[90:91], v[26:27], off offset:64
	global_load_dwordx2 v[92:93], v[26:27], off offset:96
	global_load_dwordx2 v[38:39], v[26:27], off offset:128
	global_load_dwordx2 v[40:41], v[26:27], off offset:160
	global_load_dwordx2 v[18:19], v[26:27], off offset:192
	global_load_dwordx2 v[20:21], v[26:27], off offset:224
	global_load_ushort v200, v[22:23], off
	v_mfma_f32_16x16x32_bf16 v[22:25], v[62:65], v[2:5], v[34:37]
	v_lshl_add_u64 v[26:27], s[0:1], 0, v[162:163]
	v_lshl_add_u64 v[28:29], s[0:1], 0, v[164:165]
	global_load_dword v26, v[26:27], off
	v_mfma_f32_16x16x32_bf16 v[22:25], v[58:61], v[6:9], v[22:25]
	v_lshl_add_u64 v[58:59], v[116:117], 0, s[2:3]
	global_load_dword v27, v[28:29], off
	v_lshl_add_u64 v[28:29], v[132:133], 0, s[2:3]
	v_mfma_f32_16x16x32_bf16 v[22:25], v[74:77], v[10:13], v[22:25]
	v_lshl_add_u64 v[30:31], v[134:135], 0, s[2:3]
	global_load_ushort v199, v[28:29], off
	global_load_ushort v198, v[30:31], off
	s_waitcnt vmcnt(21)
	v_mfma_f32_16x16x32_bf16 v[98:101], v[70:73], v[14:17], v[22:25]
	v_lshl_add_u64 v[28:29], s[0:1], 0, v[166:167]
	v_lshl_add_u64 v[30:31], s[0:1], 0, v[168:169]
	v_lshl_add_u64 v[70:71], v[118:119], 0, s[2:3]
	v_lshl_add_u64 v[22:23], v[136:137], 0, s[2:3]
	global_load_ushort v197, v[22:23], off
	v_add_co_u32_e32 v22, vcc, s23, v222
	global_load_dword v28, v[28:29], off
	s_nop 0
	v_addc_co_u32_e32 v23, vcc, 0, v223, vcc
	v_add_co_u32_e32 v24, vcc, s23, v58
	global_load_dword v29, v[30:31], off
	s_nop 0
	v_addc_co_u32_e32 v25, vcc, 0, v59, vcc
	global_load_dwordx2 v[86:87], v[22:23], off
	global_load_dwordx2 v[88:89], v[22:23], off offset:32
	global_load_dwordx2 v[50:51], v[24:25], off
	global_load_dwordx2 v[52:53], v[24:25], off offset:32
	v_add_co_u32_e32 v22, vcc, s23, v70
	v_lshl_add_u64 v[72:73], v[120:121], 0, s[2:3]
	s_nop 0
	v_addc_co_u32_e32 v23, vcc, 0, v71, vcc
	v_add_co_u32_e32 v24, vcc, s23, v72
	v_lshl_add_u64 v[36:37], v[146:147], 0, s[2:3]
	s_nop 0
	v_addc_co_u32_e32 v25, vcc, 0, v73, vcc
	global_load_dwordx2 v[82:83], v[22:23], off
	global_load_dwordx2 v[84:85], v[22:23], off offset:32
	global_load_dwordx2 v[42:43], v[24:25], off
	global_load_dwordx2 v[44:45], v[24:25], off offset:32
	v_lshl_add_u64 v[22:23], s[0:1], 0, v[170:171]
	global_load_dword v30, v[22:23], off
	v_lshl_add_u64 v[22:23], v[138:139], 0, s[2:3]
	global_load_ushort v196, v[22:23], off
	v_lshl_add_u64 v[22:23], s[0:1], 0, v[172:173]
	global_load_dword v31, v[22:23], off
	v_lshl_add_u64 v[22:23], v[140:141], 0, s[2:3]
	global_load_ushort v195, v[22:23], off
	v_lshl_add_u64 v[22:23], s[0:1], 0, v[174:175]
	global_load_dword v32, v[22:23], off
	v_lshl_add_u64 v[22:23], v[142:143], 0, s[2:3]
	global_load_ushort v194, v[22:23], off
	v_lshl_add_u64 v[22:23], s[0:1], 0, v[176:177]
	global_load_dword v33, v[22:23], off
	v_lshl_add_u64 v[22:23], v[144:145], 0, s[2:3]
	global_load_ushort v193, v[22:23], off
	v_add_co_u32_e32 v22, vcc, s26, v222
	v_lshl_add_u64 v[60:61], v[150:151], 0, s[2:3]
	s_nop 0
	v_addc_co_u32_e32 v23, vcc, 0, v223, vcc
	v_add_co_u32_e32 v24, vcc, s26, v58
	v_lshl_add_u64 v[34:35], s[0:1], 0, v[178:179]
	s_nop 0
	v_addc_co_u32_e32 v25, vcc, 0, v59, vcc
	global_load_dwordx2 v[78:79], v[22:23], off
	global_load_dwordx2 v[80:81], v[22:23], off offset:32
	global_load_dwordx2 v[46:47], v[24:25], off
	global_load_dwordx2 v[48:49], v[24:25], off offset:32
	v_add_co_u32_e32 v22, vcc, s26, v70
	s_lshl_b32 s8, s8, 2
	s_nop 0
	v_addc_co_u32_e32 v23, vcc, 0, v71, vcc
	v_add_co_u32_e32 v24, vcc, s26, v72
	s_add_i32 s13, s8, 0
	s_nop 0
	v_addc_co_u32_e32 v25, vcc, 0, v73, vcc
	global_load_dwordx2 v[66:67], v[22:23], off
	global_load_dwordx2 v[68:69], v[22:23], off offset:32
	s_nop 0
	global_load_dwordx2 v[22:23], v[24:25], off
	s_nop 0
	global_load_dwordx2 v[24:25], v[24:25], off offset:32
	s_add_i32 s14, s13, s12
	global_load_ushort v192, v[36:37], off
	global_load_ushort v190, v[60:61], off
	v_lshl_add_u64 v[36:37], s[0:1], 0, v[180:181]
	global_load_dword v34, v[34:35], off
	v_lshl_add_u64 v[60:61], s[0:1], 0, v[184:185]
	global_load_dword v35, v[36:37], off
	v_lshl_add_u64 v[36:37], v[148:149], 0, s[2:3]
	global_load_ushort v191, v[36:37], off
	v_lshl_add_u64 v[36:37], s[0:1], 0, v[182:183]
	global_load_dword v36, v[36:37], off
	v_lshl_add_u32 v234, v0, 7, s14
	global_load_dword v37, v[60:61], off
	v_lshl_add_u64 v[60:61], v[152:153], 0, s[2:3]
	global_load_ushort v189, v[60:61], off
	v_add_co_u32_e32 v60, vcc, s27, v222
	v_lshlrev_b32_e32 v222, 2, v220
	s_nop 0
	v_addc_co_u32_e32 v61, vcc, 0, v223, vcc
	v_add_co_u32_e32 v74, vcc, s27, v58
	v_lshl_add_u32 v222, v0, 6, v222
	s_nop 0
	v_addc_co_u32_e32 v75, vcc, 0, v59, vcc
	v_add_co_u32_e32 v70, vcc, s27, v70
	global_load_dwordx2 v[62:63], v[60:61], off
	global_load_dwordx2 v[64:65], v[60:61], off offset:32
	global_load_dwordx2 v[58:59], v[74:75], off
	s_nop 0
	global_load_dwordx2 v[60:61], v[74:75], off offset:32
	v_addc_co_u32_e32 v71, vcc, 0, v71, vcc
	v_add_co_u32_e32 v72, vcc, s27, v72
	v_xor_b32_e32 v223, 4, v222
	s_nop 0
	v_addc_co_u32_e32 v73, vcc, 0, v73, vcc
	global_load_dwordx2 v[74:75], v[70:71], off
	global_load_dwordx2 v[76:77], v[70:71], off offset:32
	s_nop 0
	global_load_dwordx2 v[70:71], v[72:73], off
	s_nop 0
	global_load_dwordx2 v[72:73], v[72:73], off offset:32
	v_xor_b32_e32 v225, 8, v222
	v_xor_b32_e32 v228, 16, v222
	v_xor_b32_e32 v229, 32, v222
	v_cmp_eq_u32_e32 vcc, 0, v220
	v_mul_f32_e32 v222, v110, v110
	v_mul_f32_e32 v224, v111, v111
	v_mul_f32_e32 v226, v112, v112
	ds_bpermute_b32 v250, v223, v222
	ds_bpermute_b32 v251, v223, v224
	ds_bpermute_b32 v252, v223, v226
	s_waitcnt lgkmcnt(0)
	v_fmac_f32_e32 v250, v110, v110
	v_fmac_f32_e32 v251, v111, v111
	v_fmac_f32_e32 v252, v112, v112
	ds_bpermute_b32 v222, v225, v250
	ds_bpermute_b32 v224, v225, v251
	ds_bpermute_b32 v226, v225, v252
	s_waitcnt lgkmcnt(0)
	v_add_f32_e32 v250, v250, v222
	v_add_f32_e32 v251, v251, v224
	v_add_f32_e32 v252, v252, v226
	ds_bpermute_b32 v222, v228, v250
	ds_bpermute_b32 v224, v228, v251
	ds_bpermute_b32 v226, v228, v252
	s_waitcnt lgkmcnt(0)
	v_add_f32_e32 v250, v250, v222
	v_add_f32_e32 v251, v251, v224
	v_add_f32_e32 v252, v252, v226
	ds_bpermute_b32 v222, v229, v250
	ds_bpermute_b32 v224, v229, v251
	ds_bpermute_b32 v226, v229, v252
	s_and_saveexec_b64 s[8:9], vcc
	s_waitcnt lgkmcnt(0)
	v_add_f32_e32 v250, v250, v222
	v_add_f32_e32 v251, v251, v224
	v_add_f32_e32 v252, v252, v226
	ds_write_b32 v234, v250
	ds_write_b32 v234, v251 offset:32
	ds_write_b32 v234, v252 offset:64
	s_or_b64 exec, exec, s[8:9]
	v_mul_f32_e32 v222, v113, v113
	v_mul_f32_e32 v224, v106, v106
	v_mul_f32_e32 v226, v107, v107
	ds_bpermute_b32 v250, v223, v222
	ds_bpermute_b32 v251, v223, v224
	ds_bpermute_b32 v252, v223, v226
	s_waitcnt lgkmcnt(0)
	v_fmac_f32_e32 v250, v113, v113
	v_fmac_f32_e32 v251, v106, v106
	v_fmac_f32_e32 v252, v107, v107
	ds_bpermute_b32 v222, v225, v250
	ds_bpermute_b32 v224, v225, v251
	ds_bpermute_b32 v226, v225, v252
	s_waitcnt lgkmcnt(0)
	v_add_f32_e32 v250, v250, v222
	v_add_f32_e32 v251, v251, v224
	v_add_f32_e32 v252, v252, v226
	ds_bpermute_b32 v222, v228, v250
	ds_bpermute_b32 v224, v228, v251
	ds_bpermute_b32 v226, v228, v252
	s_waitcnt lgkmcnt(0)
	v_add_f32_e32 v250, v250, v222
	v_add_f32_e32 v251, v251, v224
	v_add_f32_e32 v252, v252, v226
	ds_bpermute_b32 v222, v229, v250
	ds_bpermute_b32 v224, v229, v251
	ds_bpermute_b32 v226, v229, v252
	s_and_saveexec_b64 s[8:9], vcc
	s_waitcnt lgkmcnt(0)
	v_add_f32_e32 v250, v250, v222
	v_add_f32_e32 v251, v251, v224
	v_add_f32_e32 v252, v252, v226
	ds_write_b32 v234, v250 offset:96
	ds_write_b32 v234, v251 offset:512
	ds_write_b32 v234, v252 offset:544
	s_or_b64 exec, exec, s[8:9]
	v_mul_f32_e32 v222, v108, v108
	v_mul_f32_e32 v224, v109, v109
	v_mul_f32_e32 v226, v102, v102
	ds_bpermute_b32 v250, v223, v222
	ds_bpermute_b32 v251, v223, v224
	ds_bpermute_b32 v252, v223, v226
	s_waitcnt lgkmcnt(0)
	v_fmac_f32_e32 v250, v108, v108
	v_fmac_f32_e32 v251, v109, v109
	v_fmac_f32_e32 v252, v102, v102
	ds_bpermute_b32 v222, v225, v250
	ds_bpermute_b32 v224, v225, v251
	ds_bpermute_b32 v226, v225, v252
	s_waitcnt lgkmcnt(0)
	v_add_f32_e32 v250, v250, v222
	v_add_f32_e32 v251, v251, v224
	v_add_f32_e32 v252, v252, v226
	ds_bpermute_b32 v222, v228, v250
	ds_bpermute_b32 v224, v228, v251
	ds_bpermute_b32 v226, v228, v252
	s_waitcnt lgkmcnt(0)
	v_add_f32_e32 v250, v250, v222
	v_add_f32_e32 v251, v251, v224
	v_add_f32_e32 v252, v252, v226
	ds_bpermute_b32 v222, v229, v250
	ds_bpermute_b32 v224, v229, v251
	ds_bpermute_b32 v226, v229, v252
	s_and_saveexec_b64 s[8:9], vcc
	s_waitcnt lgkmcnt(0)
	v_add_f32_e32 v250, v250, v222
	v_add_f32_e32 v251, v251, v224
	v_add_f32_e32 v252, v252, v226
	ds_write_b32 v234, v250 offset:576
	ds_write_b32 v234, v251 offset:608
	ds_write_b32 v234, v252 offset:1024
	s_or_b64 exec, exec, s[8:9]
	v_mul_f32_e32 v222, v103, v103
	v_mul_f32_e32 v224, v104, v104
	v_mul_f32_e32 v226, v105, v105
	ds_bpermute_b32 v250, v223, v222
	ds_bpermute_b32 v251, v223, v224
	ds_bpermute_b32 v252, v223, v226
	s_waitcnt lgkmcnt(0)
	v_fmac_f32_e32 v250, v103, v103
	v_fmac_f32_e32 v251, v104, v104
	v_fmac_f32_e32 v252, v105, v105
	ds_bpermute_b32 v222, v225, v250
	ds_bpermute_b32 v224, v225, v251
	ds_bpermute_b32 v226, v225, v252
	s_waitcnt lgkmcnt(0)
	v_add_f32_e32 v250, v250, v222
	v_add_f32_e32 v251, v251, v224
	v_add_f32_e32 v252, v252, v226
	ds_bpermute_b32 v222, v228, v250
	ds_bpermute_b32 v224, v228, v251
	ds_bpermute_b32 v226, v228, v252
	s_waitcnt lgkmcnt(0)
	v_add_f32_e32 v250, v250, v222
	v_add_f32_e32 v251, v251, v224
	v_add_f32_e32 v252, v252, v226
	ds_bpermute_b32 v222, v229, v250
	ds_bpermute_b32 v224, v229, v251
	ds_bpermute_b32 v226, v229, v252
	s_and_saveexec_b64 s[8:9], vcc
	s_waitcnt lgkmcnt(0)
	v_add_f32_e32 v250, v250, v222
	v_add_f32_e32 v251, v251, v224
	v_add_f32_e32 v252, v252, v226
	ds_write_b32 v234, v250 offset:1056
	ds_write_b32 v234, v251 offset:1088
	ds_write_b32 v234, v252 offset:1120
	s_or_b64 exec, exec, s[8:9]
	v_mul_f32_e32 v222, v98, v98
	v_mul_f32_e32 v224, v99, v99
	v_mul_f32_e32 v226, v100, v100
	ds_bpermute_b32 v250, v223, v222
	ds_bpermute_b32 v251, v223, v224
	ds_bpermute_b32 v252, v223, v226
	s_waitcnt lgkmcnt(0)
	v_fmac_f32_e32 v250, v98, v98
	v_fmac_f32_e32 v251, v99, v99
	v_fmac_f32_e32 v252, v100, v100
	ds_bpermute_b32 v222, v225, v250
	ds_bpermute_b32 v224, v225, v251
	ds_bpermute_b32 v226, v225, v252
	s_waitcnt lgkmcnt(0)
	v_add_f32_e32 v250, v250, v222
	v_add_f32_e32 v251, v251, v224
	v_add_f32_e32 v252, v252, v226
	ds_bpermute_b32 v222, v228, v250
	ds_bpermute_b32 v224, v228, v251
	ds_bpermute_b32 v226, v228, v252
	s_waitcnt lgkmcnt(0)
	v_add_f32_e32 v250, v250, v222
	v_add_f32_e32 v251, v251, v224
	v_add_f32_e32 v252, v252, v226
	ds_bpermute_b32 v222, v229, v250
	ds_bpermute_b32 v224, v229, v251
	ds_bpermute_b32 v226, v229, v252
	s_and_saveexec_b64 s[8:9], vcc
	s_waitcnt lgkmcnt(0)
	v_add_f32_e32 v250, v250, v222
	v_add_f32_e32 v251, v251, v224
	v_add_f32_e32 v252, v252, v226
	ds_write_b32 v234, v250 offset:1536
	ds_write_b32 v234, v251 offset:1568
	ds_write_b32 v234, v252 offset:1600
	s_or_b64 exec, exec, s[8:9]
	v_mul_f32_e32 v222, v101, v101
	ds_bpermute_b32 v250, v223, v222
	s_waitcnt lgkmcnt(0)
	v_fmac_f32_e32 v250, v101, v101
	ds_bpermute_b32 v222, v225, v250
	s_waitcnt lgkmcnt(0)
	v_add_f32_e32 v250, v250, v222
	ds_bpermute_b32 v222, v228, v250
	s_waitcnt lgkmcnt(0)
	v_add_f32_e32 v250, v250, v222
	ds_bpermute_b32 v222, v229, v250
	s_and_saveexec_b64 s[8:9], vcc
	s_waitcnt lgkmcnt(0)
	v_add_f32_e32 v250, v250, v222
	ds_write_b32 v234, v250 offset:1632
	s_or_b64 exec, exec, s[8:9]
	v_lshlrev_b32_e32 v222, 2, v0
	v_add_u32_e32 v227, 16, v222
	v_add_u32_e32 v226, 32, v222
	v_add_u32_e32 v224, 48, v222
	v_add_u32_e32 v223, 51, v222
	v_lshlrev_b32_e32 v225, 5, v223
	s_mov_b64 s[8:9], exec
